# GEMM K-loops: all 16 LDS-DMA pieces per iteration now saddr+voffset (no 64-bit address VALU left; two base copies kept in spare SGPRs)
# speedup vs baseline: 1.0059x; 1.0059x over previous
.LBB0_169:
	s_add_u32 s42, s40, 0xfff80080
	s_addc_u32 s43, s41, -1
	s_add_i32 s52, 0, 0x10000
	s_cmp_eq_u32 s51, 28
	s_cselect_b32 s45, s13, s43
	s_cselect_b32 s44, s47, s42
	s_cselect_b32 s43, s11, s50
	s_cselect_b32 s42, s48, s49
	s_add_i32 s54, 0, 0x14000
	ds_read_b128 v[130:133], v236
	ds_read_b128 v[134:137], v236 offset:1024
	ds_read_b128 v[138:141], v236 offset:2048
	ds_read_b128 v[142:145], v236 offset:3072
	ds_read_b128 v[170:173], v237
	ds_read_b128 v[184:187], v237 offset:1024
	ds_read_b128 v[188:191], v237 offset:2048
	ds_read_b128 v[192:195], v237 offset:3072
	s_add_i32 m0, s14, 0xc000
	ds_read_b128 v[196:199], v183
	ds_read_b128 v[200:203], v183 offset:1024
	ds_read_b128 v[210:213], v183 offset:2048
	ds_read_b128 v[214:217], v183 offset:3072
	ds_read_b128 v[218:221], v183 offset:4096
	ds_read_b128 v[222:225], v183 offset:5120
	ds_read_b128 v[226:229], v183 offset:6144
	ds_read_b128 v[230:233], v183 offset:7168
	global_load_lds_dwordx4 v166, s[40:41]
	s_add_i32 m0, s14, 0xe000
	s_nop 0
	global_load_lds_dwordx4 v168, s[40:41]
	s_waitcnt vmcnt(8) lgkmcnt(0)
	s_barrier
	v_mfma_f32_16x16x32_bf16 v[126:129], v[130:133], v[196:199], v[126:129]
	v_mfma_f32_16x16x32_bf16 v[122:125], v[138:141], v[196:199], v[122:125]
	v_mfma_f32_16x16x32_bf16 v[118:121], v[130:133], v[210:213], v[118:121]
	v_mfma_f32_16x16x32_bf16 v[110:113], v[138:141], v[210:213], v[110:113]
	v_mfma_f32_16x16x32_bf16 v[102:105], v[130:133], v[218:221], v[102:105]
	v_mfma_f32_16x16x32_bf16 v[94:97], v[138:141], v[218:221], v[94:97]
	v_mfma_f32_16x16x32_bf16 v[86:89], v[130:133], v[226:229], v[86:89]
	v_mfma_f32_16x16x32_bf16 v[78:81], v[138:141], v[226:229], v[78:81]
	v_mfma_f32_16x16x32_bf16 v[126:129], v[134:137], v[200:203], v[126:129]
	v_mfma_f32_16x16x32_bf16 v[122:125], v[142:145], v[200:203], v[122:125]
	v_mfma_f32_16x16x32_bf16 v[118:121], v[134:137], v[214:217], v[118:121]
	v_mfma_f32_16x16x32_bf16 v[110:113], v[142:145], v[214:217], v[110:113]
	v_mfma_f32_16x16x32_bf16 v[102:105], v[134:137], v[222:225], v[102:105]
	v_mfma_f32_16x16x32_bf16 v[94:97], v[142:145], v[222:225], v[94:97]
	v_mfma_f32_16x16x32_bf16 v[86:89], v[134:137], v[230:233], v[86:89]
	v_mfma_f32_16x16x32_bf16 v[78:81], v[142:145], v[230:233], v[78:81]
	v_mfma_f32_16x16x32_bf16 v[114:117], v[170:173], v[196:199], v[114:117]
	v_mfma_f32_16x16x32_bf16 v[106:109], v[188:191], v[196:199], v[106:109]
	v_mfma_f32_16x16x32_bf16 v[98:101], v[170:173], v[210:213], v[98:101]
	v_mfma_f32_16x16x32_bf16 v[90:93], v[188:191], v[210:213], v[90:93]
	v_mfma_f32_16x16x32_bf16 v[82:85], v[170:173], v[218:221], v[82:85]
	v_mfma_f32_16x16x32_bf16 v[74:77], v[188:191], v[218:221], v[74:77]
	v_mfma_f32_16x16x32_bf16 v[70:73], v[170:173], v[226:229], v[70:73]
	v_mfma_f32_16x16x32_bf16 v[66:69], v[188:191], v[226:229], v[66:69]
	v_mfma_f32_16x16x32_bf16 v[114:117], v[184:187], v[200:203], v[114:117]
	v_mfma_f32_16x16x32_bf16 v[106:109], v[192:195], v[200:203], v[106:109]
	v_mfma_f32_16x16x32_bf16 v[98:101], v[184:187], v[214:217], v[98:101]
	v_mfma_f32_16x16x32_bf16 v[90:93], v[192:195], v[214:217], v[90:93]
	v_mfma_f32_16x16x32_bf16 v[82:85], v[184:187], v[222:225], v[82:85]
	v_mfma_f32_16x16x32_bf16 v[74:77], v[192:195], v[222:225], v[74:77]
	v_mfma_f32_16x16x32_bf16 v[70:73], v[184:187], v[230:233], v[70:73]
	v_mfma_f32_16x16x32_bf16 v[66:69], v[192:195], v[230:233], v[66:69]
	s_barrier
	s_add_i32 s52, s52, s5
	s_mov_b32 m0, s52
	ds_read_b128 v[196:199], v183 offset:16384
	ds_read_b128 v[200:203], v183 offset:17408
	ds_read_b128 v[210:213], v183 offset:18432
	ds_read_b128 v[214:217], v183 offset:19456
	ds_read_b128 v[218:221], v183 offset:20480
	ds_read_b128 v[222:225], v183 offset:21504
	ds_read_b128 v[226:229], v183 offset:22528
	ds_read_b128 v[230:233], v183 offset:23552
	global_load_lds_dwordx4 v162, s[42:43]
	s_add_i32 m0, s52, 0x2000
	s_add_u32 s52, s42, 0x80000
	s_addc_u32 s53, s43, 0
	s_add_i32 s54, s54, s5
	global_load_lds_dwordx4 v158, s[42:43]
	s_mov_b32 m0, s54
	s_nop 0
	global_load_lds_dwordx4 v162, s[52:53]
	s_add_i32 m0, s54, 0x2000
	s_nop 0
	global_load_lds_dwordx4 v158, s[52:53]
	s_mov_b32 m0, s14
	s_nop 0
	global_load_lds_dwordx4 v164, s[44:45]
	s_mov_b32 m0, s15
	s_nop 0
	global_load_lds_dwordx4 v160, s[44:45]
	s_add_u32 s98, s42, 0x80
	s_addc_u32 s99, s43, 0
	s_add_u32 s100, s44, 0x80
	s_addc_u32 s101, s45, 0
	s_waitcnt vmcnt(8) lgkmcnt(0)
	s_barrier
	v_mfma_f32_16x16x32_bf16 v[62:65], v[130:133], v[196:199], v[62:65]
	v_mfma_f32_16x16x32_bf16 v[58:61], v[138:141], v[196:199], v[58:61]
	v_mfma_f32_16x16x32_bf16 v[54:57], v[130:133], v[210:213], v[54:57]
	v_mfma_f32_16x16x32_bf16 v[46:49], v[138:141], v[210:213], v[46:49]
	v_mfma_f32_16x16x32_bf16 v[38:41], v[130:133], v[218:221], v[38:41]
	v_mfma_f32_16x16x32_bf16 v[30:33], v[138:141], v[218:221], v[30:33]
	v_mfma_f32_16x16x32_bf16 v[22:25], v[130:133], v[226:229], v[22:25]
	v_mfma_f32_16x16x32_bf16 v[14:17], v[138:141], v[226:229], v[14:17]
	v_mfma_f32_16x16x32_bf16 v[62:65], v[134:137], v[200:203], v[62:65]
	v_mfma_f32_16x16x32_bf16 v[58:61], v[142:145], v[200:203], v[58:61]
	v_mfma_f32_16x16x32_bf16 v[54:57], v[134:137], v[214:217], v[54:57]
	v_mfma_f32_16x16x32_bf16 v[46:49], v[142:145], v[214:217], v[46:49]
	v_mfma_f32_16x16x32_bf16 v[38:41], v[134:137], v[222:225], v[38:41]
	v_mfma_f32_16x16x32_bf16 v[30:33], v[142:145], v[222:225], v[30:33]
	v_mfma_f32_16x16x32_bf16 v[22:25], v[134:137], v[230:233], v[22:25]
	v_mfma_f32_16x16x32_bf16 v[14:17], v[142:145], v[230:233], v[14:17]
	v_mfma_f32_16x16x32_bf16 v[50:53], v[170:173], v[196:199], v[50:53]
	v_mfma_f32_16x16x32_bf16 v[42:45], v[188:191], v[196:199], v[42:45]
	v_mfma_f32_16x16x32_bf16 v[34:37], v[170:173], v[210:213], v[34:37]
	v_mfma_f32_16x16x32_bf16 v[26:29], v[188:191], v[210:213], v[26:29]
	v_mfma_f32_16x16x32_bf16 v[18:21], v[170:173], v[218:221], v[18:21]
	v_mfma_f32_16x16x32_bf16 v[10:13], v[188:191], v[218:221], v[10:13]
	v_mfma_f32_16x16x32_bf16 v[6:9], v[170:173], v[226:229], v[6:9]
	v_mfma_f32_16x16x32_bf16 v[2:5], v[188:191], v[226:229], v[2:5]
	v_mfma_f32_16x16x32_bf16 v[50:53], v[184:187], v[200:203], v[50:53]
	v_mfma_f32_16x16x32_bf16 v[42:45], v[192:195], v[200:203], v[42:45]
	v_mfma_f32_16x16x32_bf16 v[34:37], v[184:187], v[214:217], v[34:37]
	v_mfma_f32_16x16x32_bf16 v[26:29], v[192:195], v[214:217], v[26:29]
	v_mfma_f32_16x16x32_bf16 v[18:21], v[184:187], v[222:225], v[18:21]
	v_mfma_f32_16x16x32_bf16 v[10:13], v[192:195], v[222:225], v[10:13]
	v_mfma_f32_16x16x32_bf16 v[6:9], v[184:187], v[230:233], v[6:9]
	v_mfma_f32_16x16x32_bf16 v[2:5], v[192:195], v[230:233], v[2:5]
	s_barrier
	s_add_i32 s52, 0, 0x18000
	s_add_i32 s53, 0, 0x1c000
	ds_read_b128 v[130:133], v238
	ds_read_b128 v[134:137], v238 offset:1024
	ds_read_b128 v[138:141], v238 offset:2048
	ds_read_b128 v[142:145], v238 offset:3072
	ds_read_b128 v[170:173], v239
	ds_read_b128 v[184:187], v239 offset:1024
	ds_read_b128 v[188:191], v239 offset:2048
	ds_read_b128 v[192:195], v239 offset:3072
	s_add_u32 s44, s44, 0x80000
	s_addc_u32 s45, s45, 0
	s_mov_b32 m0, s16
	ds_read_b128 v[196:199], v183 offset:32768
	ds_read_b128 v[200:203], v183 offset:33792
	ds_read_b128 v[210:213], v183 offset:34816
	ds_read_b128 v[214:217], v183 offset:35840
	ds_read_b128 v[218:221], v183 offset:36864
	ds_read_b128 v[222:225], v183 offset:37888
	ds_read_b128 v[226:229], v183 offset:38912
	ds_read_b128 v[230:233], v183 offset:39936
	global_load_lds_dwordx4 v164, s[44:45]
	s_mov_b32 m0, s18
	s_nop 0
	global_load_lds_dwordx4 v160, s[44:45]
	s_waitcnt vmcnt(8) lgkmcnt(0)
	s_barrier
	v_mfma_f32_16x16x32_bf16 v[126:129], v[130:133], v[196:199], v[126:129]
	v_mfma_f32_16x16x32_bf16 v[122:125], v[138:141], v[196:199], v[122:125]
	v_mfma_f32_16x16x32_bf16 v[118:121], v[130:133], v[210:213], v[118:121]
	v_mfma_f32_16x16x32_bf16 v[110:113], v[138:141], v[210:213], v[110:113]
	v_mfma_f32_16x16x32_bf16 v[102:105], v[130:133], v[218:221], v[102:105]
	v_mfma_f32_16x16x32_bf16 v[94:97], v[138:141], v[218:221], v[94:97]
	v_mfma_f32_16x16x32_bf16 v[86:89], v[130:133], v[226:229], v[86:89]
	v_mfma_f32_16x16x32_bf16 v[78:81], v[138:141], v[226:229], v[78:81]
	v_mfma_f32_16x16x32_bf16 v[126:129], v[134:137], v[200:203], v[126:129]
	v_mfma_f32_16x16x32_bf16 v[122:125], v[142:145], v[200:203], v[122:125]
	v_mfma_f32_16x16x32_bf16 v[118:121], v[134:137], v[214:217], v[118:121]
	v_mfma_f32_16x16x32_bf16 v[110:113], v[142:145], v[214:217], v[110:113]
	v_mfma_f32_16x16x32_bf16 v[102:105], v[134:137], v[222:225], v[102:105]
	v_mfma_f32_16x16x32_bf16 v[94:97], v[142:145], v[222:225], v[94:97]
	v_mfma_f32_16x16x32_bf16 v[86:89], v[134:137], v[230:233], v[86:89]
	v_mfma_f32_16x16x32_bf16 v[78:81], v[142:145], v[230:233], v[78:81]
	v_mfma_f32_16x16x32_bf16 v[114:117], v[170:173], v[196:199], v[114:117]
	v_mfma_f32_16x16x32_bf16 v[106:109], v[188:191], v[196:199], v[106:109]
	v_mfma_f32_16x16x32_bf16 v[98:101], v[170:173], v[210:213], v[98:101]
	v_mfma_f32_16x16x32_bf16 v[90:93], v[188:191], v[210:213], v[90:93]
	v_mfma_f32_16x16x32_bf16 v[82:85], v[170:173], v[218:221], v[82:85]
	v_mfma_f32_16x16x32_bf16 v[74:77], v[188:191], v[218:221], v[74:77]
	v_mfma_f32_16x16x32_bf16 v[70:73], v[170:173], v[226:229], v[70:73]
	v_mfma_f32_16x16x32_bf16 v[66:69], v[188:191], v[226:229], v[66:69]
	v_mfma_f32_16x16x32_bf16 v[114:117], v[184:187], v[200:203], v[114:117]
	v_mfma_f32_16x16x32_bf16 v[106:109], v[192:195], v[200:203], v[106:109]
	v_mfma_f32_16x16x32_bf16 v[98:101], v[184:187], v[214:217], v[98:101]
	v_mfma_f32_16x16x32_bf16 v[90:93], v[192:195], v[214:217], v[90:93]
	v_mfma_f32_16x16x32_bf16 v[82:85], v[184:187], v[222:225], v[82:85]
	v_mfma_f32_16x16x32_bf16 v[74:77], v[192:195], v[222:225], v[74:77]
	v_mfma_f32_16x16x32_bf16 v[70:73], v[184:187], v[230:233], v[70:73]
	v_mfma_f32_16x16x32_bf16 v[66:69], v[192:195], v[230:233], v[66:69]
	s_barrier
	s_add_i32 s44, s52, s5
	s_mov_b32 m0, s44
	ds_read_b128 v[196:199], v183 offset:49152
	ds_read_b128 v[200:203], v183 offset:50176
	ds_read_b128 v[210:213], v183 offset:51200
	ds_read_b128 v[214:217], v183 offset:52224
	ds_read_b128 v[218:221], v183 offset:53248
	ds_read_b128 v[222:225], v183 offset:54272
	ds_read_b128 v[226:229], v183 offset:55296
	ds_read_b128 v[230:233], v183 offset:56320
	global_load_lds_dwordx4 v162, s[98:99]
	s_add_i32 m0, s44, 0x2000
	s_add_u32 s42, s42, 0x80080
	s_addc_u32 s43, s43, 0
	s_add_i32 s44, s53, s5
	global_load_lds_dwordx4 v158, s[98:99]
	s_mov_b32 m0, s44
	s_nop 0
	global_load_lds_dwordx4 v162, s[42:43]
	s_add_i32 m0, s44, 0x2000
	s_nop 0
	global_load_lds_dwordx4 v158, s[42:43]
	s_mov_b32 m0, s19
	s_nop 0
	global_load_lds_dwordx4 v164, s[100:101]
	s_mov_b32 m0, s25
	s_nop 0
	global_load_lds_dwordx4 v160, s[100:101]
	s_waitcnt vmcnt(8) lgkmcnt(0)
	s_barrier
	v_mfma_f32_16x16x32_bf16 v[62:65], v[130:133], v[196:199], v[62:65]
	v_mfma_f32_16x16x32_bf16 v[58:61], v[138:141], v[196:199], v[58:61]
	v_mfma_f32_16x16x32_bf16 v[54:57], v[130:133], v[210:213], v[54:57]
	v_mfma_f32_16x16x32_bf16 v[46:49], v[138:141], v[210:213], v[46:49]
	v_mfma_f32_16x16x32_bf16 v[38:41], v[130:133], v[218:221], v[38:41]
	v_mfma_f32_16x16x32_bf16 v[30:33], v[138:141], v[218:221], v[30:33]
	v_mfma_f32_16x16x32_bf16 v[22:25], v[130:133], v[226:229], v[22:25]
	v_mfma_f32_16x16x32_bf16 v[14:17], v[138:141], v[226:229], v[14:17]
	v_mfma_f32_16x16x32_bf16 v[62:65], v[134:137], v[200:203], v[62:65]
	v_mfma_f32_16x16x32_bf16 v[58:61], v[142:145], v[200:203], v[58:61]
	v_mfma_f32_16x16x32_bf16 v[54:57], v[134:137], v[214:217], v[54:57]
	v_mfma_f32_16x16x32_bf16 v[46:49], v[142:145], v[214:217], v[46:49]
	v_mfma_f32_16x16x32_bf16 v[38:41], v[134:137], v[222:225], v[38:41]
	v_mfma_f32_16x16x32_bf16 v[30:33], v[142:145], v[222:225], v[30:33]
	v_mfma_f32_16x16x32_bf16 v[22:25], v[134:137], v[230:233], v[22:25]
	v_mfma_f32_16x16x32_bf16 v[14:17], v[142:145], v[230:233], v[14:17]
	v_mfma_f32_16x16x32_bf16 v[50:53], v[170:173], v[196:199], v[50:53]
	v_mfma_f32_16x16x32_bf16 v[42:45], v[188:191], v[196:199], v[42:45]
	v_mfma_f32_16x16x32_bf16 v[34:37], v[170:173], v[210:213], v[34:37]
	v_mfma_f32_16x16x32_bf16 v[26:29], v[188:191], v[210:213], v[26:29]
	v_mfma_f32_16x16x32_bf16 v[18:21], v[170:173], v[218:221], v[18:21]
	v_mfma_f32_16x16x32_bf16 v[10:13], v[188:191], v[218:221], v[10:13]
	v_mfma_f32_16x16x32_bf16 v[6:9], v[170:173], v[226:229], v[6:9]
	v_mfma_f32_16x16x32_bf16 v[2:5], v[188:191], v[226:229], v[2:5]
	v_mfma_f32_16x16x32_bf16 v[50:53], v[184:187], v[200:203], v[50:53]
	v_mfma_f32_16x16x32_bf16 v[42:45], v[192:195], v[200:203], v[42:45]
	v_mfma_f32_16x16x32_bf16 v[34:37], v[184:187], v[214:217], v[34:37]
	v_mfma_f32_16x16x32_bf16 v[26:29], v[192:195], v[214:217], v[26:29]
	v_mfma_f32_16x16x32_bf16 v[18:21], v[184:187], v[222:225], v[18:21]
	v_mfma_f32_16x16x32_bf16 v[10:13], v[192:195], v[222:225], v[10:13]
	v_mfma_f32_16x16x32_bf16 v[6:9], v[184:187], v[230:233], v[6:9]
	v_mfma_f32_16x16x32_bf16 v[2:5], v[192:195], v[230:233], v[2:5]
	s_barrier
	s_add_i32 s51, s51, 2
	s_add_u32 s40, s40, 0x100
	s_addc_u32 s41, s41, 0
	s_add_u32 s49, s49, 0x100
	s_addc_u32 s50, s50, 0
	s_cmp_gt_u32 s51, 29
	s_cbranch_scc0 .LBB0_169
	s_setprio 0
	s_and_b64 vcc, exec, s[8:9]
	s_cbranch_vccz .LBB0_172
	s_barrier

.LBB0_516:
	s_add_u32 s46, s44, 0xfff80080
	s_addc_u32 s47, s45, -1
	s_add_i32 s58, 0, 0x10000
	s_cmp_eq_u32 s57, 28
	s_cselect_b32 s49, s21, s47
	s_cselect_b32 s48, s50, s46
	s_cselect_b32 s47, s13, s56
	s_cselect_b32 s46, s51, s55
	s_add_i32 s60, 0, 0x14000
	ds_read_b128 v[82:85], v236
	ds_read_b128 v[86:89], v236 offset:1024
	ds_read_b128 v[98:101], v236 offset:2048
	ds_read_b128 v[102:105], v236 offset:3072
	ds_read_b128 v[154:157], v237
	ds_read_b128 v[168:171], v237 offset:1024
	ds_read_b128 v[176:179], v237 offset:2048
	ds_read_b128 v[180:183], v237 offset:3072
	s_add_i32 m0, s14, 0xc000
	ds_read_b128 v[184:187], v174
	ds_read_b128 v[188:191], v174 offset:1024
	ds_read_b128 v[192:195], v174 offset:2048
	ds_read_b128 v[196:199], v174 offset:3072
	ds_read_b128 v[200:203], v174 offset:4096
	ds_read_b128 v[210:213], v174 offset:5120
	ds_read_b128 v[214:217], v174 offset:6144
	ds_read_b128 v[218:221], v174 offset:7168
	global_load_lds_dwordx4 v164, s[44:45]
	s_add_i32 m0, s14, 0xe000
	s_nop 0
	global_load_lds_dwordx4 v166, s[44:45]
	s_waitcnt vmcnt(8) lgkmcnt(0)
	s_barrier
	v_mfma_f32_16x16x32_bf16 v[142:145], v[82:85], v[184:187], v[142:145]
	v_mfma_f32_16x16x32_bf16 v[138:141], v[98:101], v[184:187], v[138:141]
	v_mfma_f32_16x16x32_bf16 v[126:129], v[82:85], v[192:195], v[126:129]
	v_mfma_f32_16x16x32_bf16 v[122:125], v[98:101], v[192:195], v[122:125]
	v_mfma_f32_16x16x32_bf16 v[110:113], v[82:85], v[200:203], v[110:113]
	v_mfma_f32_16x16x32_bf16 v[106:109], v[98:101], v[200:203], v[106:109]
	v_mfma_f32_16x16x32_bf16 v[78:81], v[82:85], v[214:217], v[78:81]
	v_mfma_f32_16x16x32_bf16 v[74:77], v[98:101], v[214:217], v[74:77]
	v_mfma_f32_16x16x32_bf16 v[142:145], v[86:89], v[188:191], v[142:145]
	v_mfma_f32_16x16x32_bf16 v[138:141], v[102:105], v[188:191], v[138:141]
	v_mfma_f32_16x16x32_bf16 v[126:129], v[86:89], v[196:199], v[126:129]
	v_mfma_f32_16x16x32_bf16 v[122:125], v[102:105], v[196:199], v[122:125]
	v_mfma_f32_16x16x32_bf16 v[110:113], v[86:89], v[210:213], v[110:113]
	v_mfma_f32_16x16x32_bf16 v[106:109], v[102:105], v[210:213], v[106:109]
	v_mfma_f32_16x16x32_bf16 v[78:81], v[86:89], v[218:221], v[78:81]
	v_mfma_f32_16x16x32_bf16 v[74:77], v[102:105], v[218:221], v[74:77]
	v_mfma_f32_16x16x32_bf16 v[134:137], v[154:157], v[184:187], v[134:137]
	v_mfma_f32_16x16x32_bf16 v[130:133], v[176:179], v[184:187], v[130:133]
	v_mfma_f32_16x16x32_bf16 v[118:121], v[154:157], v[192:195], v[118:121]
	v_mfma_f32_16x16x32_bf16 v[114:117], v[176:179], v[192:195], v[114:117]
	v_mfma_f32_16x16x32_bf16 v[94:97], v[154:157], v[200:203], v[94:97]
	v_mfma_f32_16x16x32_bf16 v[90:93], v[176:179], v[200:203], v[90:93]
	v_mfma_f32_16x16x32_bf16 v[70:73], v[154:157], v[214:217], v[70:73]
	v_mfma_f32_16x16x32_bf16 v[66:69], v[176:179], v[214:217], v[66:69]
	v_mfma_f32_16x16x32_bf16 v[134:137], v[168:171], v[188:191], v[134:137]
	v_mfma_f32_16x16x32_bf16 v[130:133], v[180:183], v[188:191], v[130:133]
	v_mfma_f32_16x16x32_bf16 v[118:121], v[168:171], v[196:199], v[118:121]
	v_mfma_f32_16x16x32_bf16 v[114:117], v[180:183], v[196:199], v[114:117]
	v_mfma_f32_16x16x32_bf16 v[94:97], v[168:171], v[210:213], v[94:97]
	v_mfma_f32_16x16x32_bf16 v[90:93], v[180:183], v[210:213], v[90:93]
	v_mfma_f32_16x16x32_bf16 v[70:73], v[168:171], v[218:221], v[70:73]
	v_mfma_f32_16x16x32_bf16 v[66:69], v[180:183], v[218:221], v[66:69]
	s_barrier
	s_add_i32 s58, s58, s5
	s_mov_b32 m0, s58
	ds_read_b128 v[184:187], v174 offset:16384
	ds_read_b128 v[188:191], v174 offset:17408
	ds_read_b128 v[192:195], v174 offset:18432
	ds_read_b128 v[196:199], v174 offset:19456
	ds_read_b128 v[200:203], v174 offset:20480
	ds_read_b128 v[210:213], v174 offset:21504
	ds_read_b128 v[214:217], v174 offset:22528
	ds_read_b128 v[218:221], v174 offset:23552
	global_load_lds_dwordx4 v0, s[46:47]
	s_add_i32 m0, s58, 0x2000
	s_add_u32 s58, s46, 0x80000
	s_addc_u32 s59, s47, 0
	s_add_i32 s60, s60, s5
	global_load_lds_dwordx4 v158, s[46:47]
	s_mov_b32 m0, s60
	s_nop 0
	global_load_lds_dwordx4 v0, s[58:59]
	s_add_i32 m0, s60, 0x2000
	s_nop 0
	global_load_lds_dwordx4 v158, s[58:59]
	s_mov_b32 m0, s14
	s_nop 0
	global_load_lds_dwordx4 v162, s[48:49]
	s_mov_b32 m0, s15
	s_nop 0
	global_load_lds_dwordx4 v160, s[48:49]
	s_add_u32 s98, s46, 0x80
	s_addc_u32 s99, s47, 0
	s_add_u32 s100, s48, 0x80
	s_addc_u32 s101, s49, 0
	s_waitcnt vmcnt(8) lgkmcnt(0)
	s_barrier
	v_mfma_f32_16x16x32_bf16 v[62:65], v[82:85], v[184:187], v[62:65]
	v_mfma_f32_16x16x32_bf16 v[58:61], v[98:101], v[184:187], v[58:61]
	v_mfma_f32_16x16x32_bf16 v[46:49], v[82:85], v[192:195], v[46:49]
	v_mfma_f32_16x16x32_bf16 v[42:45], v[98:101], v[192:195], v[42:45]
	v_mfma_f32_16x16x32_bf16 v[30:33], v[82:85], v[200:203], v[30:33]
	v_mfma_f32_16x16x32_bf16 v[26:29], v[98:101], v[200:203], v[26:29]
	v_mfma_f32_16x16x32_bf16 v[14:17], v[82:85], v[214:217], v[14:17]
	v_mfma_f32_16x16x32_bf16 v[10:13], v[98:101], v[214:217], v[10:13]
	v_mfma_f32_16x16x32_bf16 v[62:65], v[86:89], v[188:191], v[62:65]
	v_mfma_f32_16x16x32_bf16 v[58:61], v[102:105], v[188:191], v[58:61]
	v_mfma_f32_16x16x32_bf16 v[46:49], v[86:89], v[196:199], v[46:49]
	v_mfma_f32_16x16x32_bf16 v[42:45], v[102:105], v[196:199], v[42:45]
	v_mfma_f32_16x16x32_bf16 v[30:33], v[86:89], v[210:213], v[30:33]
	v_mfma_f32_16x16x32_bf16 v[26:29], v[102:105], v[210:213], v[26:29]
	v_mfma_f32_16x16x32_bf16 v[14:17], v[86:89], v[218:221], v[14:17]
	v_mfma_f32_16x16x32_bf16 v[10:13], v[102:105], v[218:221], v[10:13]
	v_mfma_f32_16x16x32_bf16 v[54:57], v[154:157], v[184:187], v[54:57]
	v_mfma_f32_16x16x32_bf16 v[50:53], v[176:179], v[184:187], v[50:53]
	v_mfma_f32_16x16x32_bf16 v[38:41], v[154:157], v[192:195], v[38:41]
	v_mfma_f32_16x16x32_bf16 v[34:37], v[176:179], v[192:195], v[34:37]
	v_mfma_f32_16x16x32_bf16 v[22:25], v[154:157], v[200:203], v[22:25]
	v_mfma_f32_16x16x32_bf16 v[18:21], v[176:179], v[200:203], v[18:21]
	v_mfma_f32_16x16x32_bf16 v[6:9], v[154:157], v[214:217], v[6:9]
	v_mfma_f32_16x16x32_bf16 v[2:5], v[176:179], v[214:217], v[2:5]
	v_mfma_f32_16x16x32_bf16 v[54:57], v[168:171], v[188:191], v[54:57]
	v_mfma_f32_16x16x32_bf16 v[50:53], v[180:183], v[188:191], v[50:53]
	v_mfma_f32_16x16x32_bf16 v[38:41], v[168:171], v[196:199], v[38:41]
	v_mfma_f32_16x16x32_bf16 v[34:37], v[180:183], v[196:199], v[34:37]
	v_mfma_f32_16x16x32_bf16 v[22:25], v[168:171], v[210:213], v[22:25]
	v_mfma_f32_16x16x32_bf16 v[18:21], v[180:183], v[210:213], v[18:21]
	v_mfma_f32_16x16x32_bf16 v[6:9], v[168:171], v[218:221], v[6:9]
	v_mfma_f32_16x16x32_bf16 v[2:5], v[180:183], v[218:221], v[2:5]
	s_barrier
	s_add_i32 s58, 0, 0x18000
	s_add_i32 s59, 0, 0x1c000
	ds_read_b128 v[82:85], v238
	ds_read_b128 v[86:89], v238 offset:1024
	ds_read_b128 v[98:101], v238 offset:2048
	ds_read_b128 v[102:105], v238 offset:3072
	ds_read_b128 v[154:157], v239
	ds_read_b128 v[168:171], v239 offset:1024
	ds_read_b128 v[176:179], v239 offset:2048
	ds_read_b128 v[180:183], v239 offset:3072
	s_add_u32 s48, s48, 0x80000
	s_addc_u32 s49, s49, 0
	s_mov_b32 m0, s16
	ds_read_b128 v[184:187], v174 offset:32768
	ds_read_b128 v[188:191], v174 offset:33792
	ds_read_b128 v[192:195], v174 offset:34816
	ds_read_b128 v[196:199], v174 offset:35840
	ds_read_b128 v[200:203], v174 offset:36864
	ds_read_b128 v[210:213], v174 offset:37888
	ds_read_b128 v[214:217], v174 offset:38912
	ds_read_b128 v[218:221], v174 offset:39936
	global_load_lds_dwordx4 v162, s[48:49]
	s_mov_b32 m0, s18
	s_nop 0
	global_load_lds_dwordx4 v160, s[48:49]
	s_waitcnt vmcnt(8) lgkmcnt(0)
	s_barrier
	v_mfma_f32_16x16x32_bf16 v[142:145], v[82:85], v[184:187], v[142:145]
	v_mfma_f32_16x16x32_bf16 v[138:141], v[98:101], v[184:187], v[138:141]
	v_mfma_f32_16x16x32_bf16 v[126:129], v[82:85], v[192:195], v[126:129]
	v_mfma_f32_16x16x32_bf16 v[122:125], v[98:101], v[192:195], v[122:125]
	v_mfma_f32_16x16x32_bf16 v[110:113], v[82:85], v[200:203], v[110:113]
	v_mfma_f32_16x16x32_bf16 v[106:109], v[98:101], v[200:203], v[106:109]
	v_mfma_f32_16x16x32_bf16 v[78:81], v[82:85], v[214:217], v[78:81]
	v_mfma_f32_16x16x32_bf16 v[74:77], v[98:101], v[214:217], v[74:77]
	v_mfma_f32_16x16x32_bf16 v[142:145], v[86:89], v[188:191], v[142:145]
	v_mfma_f32_16x16x32_bf16 v[138:141], v[102:105], v[188:191], v[138:141]
	v_mfma_f32_16x16x32_bf16 v[126:129], v[86:89], v[196:199], v[126:129]
	v_mfma_f32_16x16x32_bf16 v[122:125], v[102:105], v[196:199], v[122:125]
	v_mfma_f32_16x16x32_bf16 v[110:113], v[86:89], v[210:213], v[110:113]
	v_mfma_f32_16x16x32_bf16 v[106:109], v[102:105], v[210:213], v[106:109]
	v_mfma_f32_16x16x32_bf16 v[78:81], v[86:89], v[218:221], v[78:81]
	v_mfma_f32_16x16x32_bf16 v[74:77], v[102:105], v[218:221], v[74:77]
	v_mfma_f32_16x16x32_bf16 v[134:137], v[154:157], v[184:187], v[134:137]
	v_mfma_f32_16x16x32_bf16 v[130:133], v[176:179], v[184:187], v[130:133]
	v_mfma_f32_16x16x32_bf16 v[118:121], v[154:157], v[192:195], v[118:121]
	v_mfma_f32_16x16x32_bf16 v[114:117], v[176:179], v[192:195], v[114:117]
	v_mfma_f32_16x16x32_bf16 v[94:97], v[154:157], v[200:203], v[94:97]
	v_mfma_f32_16x16x32_bf16 v[90:93], v[176:179], v[200:203], v[90:93]
	v_mfma_f32_16x16x32_bf16 v[70:73], v[154:157], v[214:217], v[70:73]
	v_mfma_f32_16x16x32_bf16 v[66:69], v[176:179], v[214:217], v[66:69]
	v_mfma_f32_16x16x32_bf16 v[134:137], v[168:171], v[188:191], v[134:137]
	v_mfma_f32_16x16x32_bf16 v[130:133], v[180:183], v[188:191], v[130:133]
	v_mfma_f32_16x16x32_bf16 v[118:121], v[168:171], v[196:199], v[118:121]
	v_mfma_f32_16x16x32_bf16 v[114:117], v[180:183], v[196:199], v[114:117]
	v_mfma_f32_16x16x32_bf16 v[94:97], v[168:171], v[210:213], v[94:97]
	v_mfma_f32_16x16x32_bf16 v[90:93], v[180:183], v[210:213], v[90:93]
	v_mfma_f32_16x16x32_bf16 v[70:73], v[168:171], v[218:221], v[70:73]
	v_mfma_f32_16x16x32_bf16 v[66:69], v[180:183], v[218:221], v[66:69]
	s_barrier
	s_add_i32 s48, s58, s5
	s_mov_b32 m0, s48
	ds_read_b128 v[184:187], v174 offset:49152
	ds_read_b128 v[188:191], v174 offset:50176
	ds_read_b128 v[192:195], v174 offset:51200
	ds_read_b128 v[196:199], v174 offset:52224
	ds_read_b128 v[200:203], v174 offset:53248
	ds_read_b128 v[210:213], v174 offset:54272
	ds_read_b128 v[214:217], v174 offset:55296
	ds_read_b128 v[218:221], v174 offset:56320
	global_load_lds_dwordx4 v0, s[98:99]
	s_add_i32 m0, s48, 0x2000
	s_add_u32 s46, s46, 0x80080
	s_addc_u32 s47, s47, 0
	s_add_i32 s48, s59, s5
	global_load_lds_dwordx4 v158, s[98:99]
	s_mov_b32 m0, s48
	s_nop 0
	global_load_lds_dwordx4 v0, s[46:47]
	s_add_i32 m0, s48, 0x2000
	s_nop 0
	global_load_lds_dwordx4 v158, s[46:47]
	s_mov_b32 m0, s25
	s_nop 0
	global_load_lds_dwordx4 v162, s[100:101]
	s_mov_b32 m0, s33
	s_nop 0
	global_load_lds_dwordx4 v160, s[100:101]
	s_waitcnt vmcnt(8) lgkmcnt(0)
	s_barrier
	v_mfma_f32_16x16x32_bf16 v[62:65], v[82:85], v[184:187], v[62:65]
	v_mfma_f32_16x16x32_bf16 v[58:61], v[98:101], v[184:187], v[58:61]
	v_mfma_f32_16x16x32_bf16 v[46:49], v[82:85], v[192:195], v[46:49]
	v_mfma_f32_16x16x32_bf16 v[42:45], v[98:101], v[192:195], v[42:45]
	v_mfma_f32_16x16x32_bf16 v[30:33], v[82:85], v[200:203], v[30:33]
	v_mfma_f32_16x16x32_bf16 v[26:29], v[98:101], v[200:203], v[26:29]
	v_mfma_f32_16x16x32_bf16 v[14:17], v[82:85], v[214:217], v[14:17]
	v_mfma_f32_16x16x32_bf16 v[10:13], v[98:101], v[214:217], v[10:13]
	v_mfma_f32_16x16x32_bf16 v[62:65], v[86:89], v[188:191], v[62:65]
	v_mfma_f32_16x16x32_bf16 v[58:61], v[102:105], v[188:191], v[58:61]
	v_mfma_f32_16x16x32_bf16 v[46:49], v[86:89], v[196:199], v[46:49]
	v_mfma_f32_16x16x32_bf16 v[42:45], v[102:105], v[196:199], v[42:45]
	v_mfma_f32_16x16x32_bf16 v[30:33], v[86:89], v[210:213], v[30:33]
	v_mfma_f32_16x16x32_bf16 v[26:29], v[102:105], v[210:213], v[26:29]
	v_mfma_f32_16x16x32_bf16 v[14:17], v[86:89], v[218:221], v[14:17]
	v_mfma_f32_16x16x32_bf16 v[10:13], v[102:105], v[218:221], v[10:13]
	v_mfma_f32_16x16x32_bf16 v[54:57], v[154:157], v[184:187], v[54:57]
	v_mfma_f32_16x16x32_bf16 v[50:53], v[176:179], v[184:187], v[50:53]
	v_mfma_f32_16x16x32_bf16 v[38:41], v[154:157], v[192:195], v[38:41]
	v_mfma_f32_16x16x32_bf16 v[34:37], v[176:179], v[192:195], v[34:37]
	v_mfma_f32_16x16x32_bf16 v[22:25], v[154:157], v[200:203], v[22:25]
	v_mfma_f32_16x16x32_bf16 v[18:21], v[176:179], v[200:203], v[18:21]
	v_mfma_f32_16x16x32_bf16 v[6:9], v[154:157], v[214:217], v[6:9]
	v_mfma_f32_16x16x32_bf16 v[2:5], v[176:179], v[214:217], v[2:5]
	v_mfma_f32_16x16x32_bf16 v[54:57], v[168:171], v[188:191], v[54:57]
	v_mfma_f32_16x16x32_bf16 v[50:53], v[180:183], v[188:191], v[50:53]
	v_mfma_f32_16x16x32_bf16 v[38:41], v[168:171], v[196:199], v[38:41]
	v_mfma_f32_16x16x32_bf16 v[34:37], v[180:183], v[196:199], v[34:37]
	v_mfma_f32_16x16x32_bf16 v[22:25], v[168:171], v[210:213], v[22:25]
	v_mfma_f32_16x16x32_bf16 v[18:21], v[180:183], v[210:213], v[18:21]
	v_mfma_f32_16x16x32_bf16 v[6:9], v[168:171], v[218:221], v[6:9]
	v_mfma_f32_16x16x32_bf16 v[2:5], v[180:183], v[218:221], v[2:5]
	s_barrier
	s_add_i32 s57, s57, 2
	s_add_u32 s44, s44, 0x100
	s_addc_u32 s45, s45, 0
	s_add_u32 s55, s55, 0x100
	s_addc_u32 s56, s56, 0
	s_cmp_gt_u32 s57, 29
	s_cbranch_scc0 .LBB0_516
	s_setprio 0
	s_and_b64 vcc, exec, s[10:11]
	s_cbranch_vccz .LBB0_519
	s_barrier

.LBB0_604:
	s_add_u32 s22, s6, 0xfff80080
	s_addc_u32 s23, s7, -1
	s_add_i32 s54, 0, 0x10000
	s_cmp_eq_u32 s53, 28
	s_cselect_b32 s47, s18, s23
	s_cselect_b32 s46, s19, s22
	s_cselect_b32 s23, s21, s52
	s_cselect_b32 s22, s25, s41
	s_add_i32 s56, 0, 0x14000
	ds_read_b128 v[130:133], v236
	ds_read_b128 v[134:137], v236 offset:1024
	ds_read_b128 v[154:157], v236 offset:2048
	ds_read_b128 v[162:165], v236 offset:3072
	ds_read_b128 v[166:169], v237
	ds_read_b128 v[170:173], v237 offset:1024
	ds_read_b128 v[180:183], v237 offset:2048
	ds_read_b128 v[184:187], v237 offset:3072
	s_add_i32 m0, s16, 0xc000
	ds_read_b128 v[188:191], v179
	ds_read_b128 v[192:195], v179 offset:1024
	ds_read_b128 v[196:199], v179 offset:2048
	ds_read_b128 v[200:203], v179 offset:3072
	ds_read_b128 v[210:213], v179 offset:4096
	ds_read_b128 v[214:217], v179 offset:5120
	ds_read_b128 v[218:221], v179 offset:6144
	ds_read_b128 v[222:225], v179 offset:7168
	global_load_lds_dwordx4 v158, s[6:7]
	s_add_i32 m0, s16, 0xe000
	s_nop 0
	global_load_lds_dwordx4 v160, s[6:7]
	s_waitcnt vmcnt(8) lgkmcnt(0)
	s_barrier
	v_mfma_f32_16x16x32_bf16 v[126:129], v[130:133], v[188:191], v[126:129]
	v_mfma_f32_16x16x32_bf16 v[122:125], v[154:157], v[188:191], v[122:125]
	v_mfma_f32_16x16x32_bf16 v[110:113], v[130:133], v[196:199], v[110:113]
	v_mfma_f32_16x16x32_bf16 v[106:109], v[154:157], v[196:199], v[106:109]
	v_mfma_f32_16x16x32_bf16 v[94:97], v[130:133], v[210:213], v[94:97]
	v_mfma_f32_16x16x32_bf16 v[90:93], v[154:157], v[210:213], v[90:93]
	v_mfma_f32_16x16x32_bf16 v[78:81], v[130:133], v[218:221], v[78:81]
	v_mfma_f32_16x16x32_bf16 v[74:77], v[154:157], v[218:221], v[74:77]
	v_mfma_f32_16x16x32_bf16 v[126:129], v[134:137], v[192:195], v[126:129]
	v_mfma_f32_16x16x32_bf16 v[122:125], v[162:165], v[192:195], v[122:125]
	v_mfma_f32_16x16x32_bf16 v[110:113], v[134:137], v[200:203], v[110:113]
	v_mfma_f32_16x16x32_bf16 v[106:109], v[162:165], v[200:203], v[106:109]
	v_mfma_f32_16x16x32_bf16 v[94:97], v[134:137], v[214:217], v[94:97]
	v_mfma_f32_16x16x32_bf16 v[90:93], v[162:165], v[214:217], v[90:93]
	v_mfma_f32_16x16x32_bf16 v[78:81], v[134:137], v[222:225], v[78:81]
	v_mfma_f32_16x16x32_bf16 v[74:77], v[162:165], v[222:225], v[74:77]
	v_mfma_f32_16x16x32_bf16 v[118:121], v[166:169], v[188:191], v[118:121]
	v_mfma_f32_16x16x32_bf16 v[114:117], v[180:183], v[188:191], v[114:117]
	v_mfma_f32_16x16x32_bf16 v[102:105], v[166:169], v[196:199], v[102:105]
	v_mfma_f32_16x16x32_bf16 v[98:101], v[180:183], v[196:199], v[98:101]
	v_mfma_f32_16x16x32_bf16 v[86:89], v[166:169], v[210:213], v[86:89]
	v_mfma_f32_16x16x32_bf16 v[82:85], v[180:183], v[210:213], v[82:85]
	v_mfma_f32_16x16x32_bf16 v[70:73], v[166:169], v[218:221], v[70:73]
	v_mfma_f32_16x16x32_bf16 v[66:69], v[180:183], v[218:221], v[66:69]
	v_mfma_f32_16x16x32_bf16 v[118:121], v[170:173], v[192:195], v[118:121]
	v_mfma_f32_16x16x32_bf16 v[114:117], v[184:187], v[192:195], v[114:117]
	v_mfma_f32_16x16x32_bf16 v[102:105], v[170:173], v[200:203], v[102:105]
	v_mfma_f32_16x16x32_bf16 v[98:101], v[184:187], v[200:203], v[98:101]
	v_mfma_f32_16x16x32_bf16 v[86:89], v[170:173], v[214:217], v[86:89]
	v_mfma_f32_16x16x32_bf16 v[82:85], v[184:187], v[214:217], v[82:85]
	v_mfma_f32_16x16x32_bf16 v[70:73], v[170:173], v[222:225], v[70:73]
	v_mfma_f32_16x16x32_bf16 v[66:69], v[184:187], v[222:225], v[66:69]
	s_barrier
	s_add_i32 s54, s54, s15
	s_mov_b32 m0, s54
	ds_read_b128 v[188:191], v179 offset:16384
	ds_read_b128 v[192:195], v179 offset:17408
	ds_read_b128 v[196:199], v179 offset:18432
	ds_read_b128 v[200:203], v179 offset:19456
	ds_read_b128 v[210:213], v179 offset:20480
	ds_read_b128 v[214:217], v179 offset:21504
	ds_read_b128 v[218:221], v179 offset:22528
	ds_read_b128 v[222:225], v179 offset:23552
	global_load_lds_dwordx4 v142, s[22:23]
	s_add_i32 m0, s54, 0x2000
	s_add_u32 s54, s22, 0x80000
	s_addc_u32 s55, s23, 0
	s_add_i32 s56, s56, s15
	global_load_lds_dwordx4 v138, s[22:23]
	s_mov_b32 m0, s56
	s_nop 0
	global_load_lds_dwordx4 v142, s[54:55]
	s_add_i32 m0, s56, 0x2000
	s_nop 0
	global_load_lds_dwordx4 v138, s[54:55]
	s_mov_b32 m0, s16
	s_nop 0
	global_load_lds_dwordx4 v144, s[46:47]
	s_mov_b32 m0, s33
	s_nop 0
	global_load_lds_dwordx4 v140, s[46:47]
	s_add_u32 s98, s22, 0x80
	s_addc_u32 s99, s23, 0
	s_add_u32 s100, s46, 0x80
	s_addc_u32 s101, s47, 0
	s_waitcnt vmcnt(8) lgkmcnt(0)
	s_barrier
	v_mfma_f32_16x16x32_bf16 v[62:65], v[130:133], v[188:191], v[62:65]
	v_mfma_f32_16x16x32_bf16 v[58:61], v[154:157], v[188:191], v[58:61]
	v_mfma_f32_16x16x32_bf16 v[46:49], v[130:133], v[196:199], v[46:49]
	v_mfma_f32_16x16x32_bf16 v[42:45], v[154:157], v[196:199], v[42:45]
	v_mfma_f32_16x16x32_bf16 v[30:33], v[130:133], v[210:213], v[30:33]
	v_mfma_f32_16x16x32_bf16 v[26:29], v[154:157], v[210:213], v[26:29]
	v_mfma_f32_16x16x32_bf16 v[14:17], v[130:133], v[218:221], v[14:17]
	v_mfma_f32_16x16x32_bf16 v[10:13], v[154:157], v[218:221], v[10:13]
	v_mfma_f32_16x16x32_bf16 v[62:65], v[134:137], v[192:195], v[62:65]
	v_mfma_f32_16x16x32_bf16 v[58:61], v[162:165], v[192:195], v[58:61]
	v_mfma_f32_16x16x32_bf16 v[46:49], v[134:137], v[200:203], v[46:49]
	v_mfma_f32_16x16x32_bf16 v[42:45], v[162:165], v[200:203], v[42:45]
	v_mfma_f32_16x16x32_bf16 v[30:33], v[134:137], v[214:217], v[30:33]
	v_mfma_f32_16x16x32_bf16 v[26:29], v[162:165], v[214:217], v[26:29]
	v_mfma_f32_16x16x32_bf16 v[14:17], v[134:137], v[222:225], v[14:17]
	v_mfma_f32_16x16x32_bf16 v[10:13], v[162:165], v[222:225], v[10:13]
	v_mfma_f32_16x16x32_bf16 v[54:57], v[166:169], v[188:191], v[54:57]
	v_mfma_f32_16x16x32_bf16 v[50:53], v[180:183], v[188:191], v[50:53]
	v_mfma_f32_16x16x32_bf16 v[38:41], v[166:169], v[196:199], v[38:41]
	v_mfma_f32_16x16x32_bf16 v[34:37], v[180:183], v[196:199], v[34:37]
	v_mfma_f32_16x16x32_bf16 v[22:25], v[166:169], v[210:213], v[22:25]
	v_mfma_f32_16x16x32_bf16 v[18:21], v[180:183], v[210:213], v[18:21]
	v_mfma_f32_16x16x32_bf16 v[6:9], v[166:169], v[218:221], v[6:9]
	v_mfma_f32_16x16x32_bf16 v[2:5], v[180:183], v[218:221], v[2:5]
	v_mfma_f32_16x16x32_bf16 v[54:57], v[170:173], v[192:195], v[54:57]
	v_mfma_f32_16x16x32_bf16 v[50:53], v[184:187], v[192:195], v[50:53]
	v_mfma_f32_16x16x32_bf16 v[38:41], v[170:173], v[200:203], v[38:41]
	v_mfma_f32_16x16x32_bf16 v[34:37], v[184:187], v[200:203], v[34:37]
	v_mfma_f32_16x16x32_bf16 v[22:25], v[170:173], v[214:217], v[22:25]
	v_mfma_f32_16x16x32_bf16 v[18:21], v[184:187], v[214:217], v[18:21]
	v_mfma_f32_16x16x32_bf16 v[6:9], v[170:173], v[222:225], v[6:9]
	v_mfma_f32_16x16x32_bf16 v[2:5], v[184:187], v[222:225], v[2:5]
	s_barrier
	s_add_i32 s54, 0, 0x18000
	s_add_i32 s55, 0, 0x1c000
	ds_read_b128 v[130:133], v238
	ds_read_b128 v[134:137], v238 offset:1024
	ds_read_b128 v[154:157], v238 offset:2048
	ds_read_b128 v[162:165], v238 offset:3072
	ds_read_b128 v[166:169], v239
	ds_read_b128 v[170:173], v239 offset:1024
	ds_read_b128 v[180:183], v239 offset:2048
	ds_read_b128 v[184:187], v239 offset:3072
	s_add_u32 s46, s46, 0x80000
	s_addc_u32 s47, s47, 0
	s_mov_b32 m0, s37
	ds_read_b128 v[188:191], v179 offset:32768
	ds_read_b128 v[192:195], v179 offset:33792
	ds_read_b128 v[196:199], v179 offset:34816
	ds_read_b128 v[200:203], v179 offset:35840
	ds_read_b128 v[210:213], v179 offset:36864
	ds_read_b128 v[214:217], v179 offset:37888
	ds_read_b128 v[218:221], v179 offset:38912
	ds_read_b128 v[222:225], v179 offset:39936
	global_load_lds_dwordx4 v144, s[46:47]
	s_mov_b32 m0, s48
	s_nop 0
	global_load_lds_dwordx4 v140, s[46:47]
	s_waitcnt vmcnt(8) lgkmcnt(0)
	s_barrier
	v_mfma_f32_16x16x32_bf16 v[126:129], v[130:133], v[188:191], v[126:129]
	v_mfma_f32_16x16x32_bf16 v[122:125], v[154:157], v[188:191], v[122:125]
	v_mfma_f32_16x16x32_bf16 v[110:113], v[130:133], v[196:199], v[110:113]
	v_mfma_f32_16x16x32_bf16 v[106:109], v[154:157], v[196:199], v[106:109]
	v_mfma_f32_16x16x32_bf16 v[94:97], v[130:133], v[210:213], v[94:97]
	v_mfma_f32_16x16x32_bf16 v[90:93], v[154:157], v[210:213], v[90:93]
	v_mfma_f32_16x16x32_bf16 v[78:81], v[130:133], v[218:221], v[78:81]
	v_mfma_f32_16x16x32_bf16 v[74:77], v[154:157], v[218:221], v[74:77]
	v_mfma_f32_16x16x32_bf16 v[126:129], v[134:137], v[192:195], v[126:129]
	v_mfma_f32_16x16x32_bf16 v[122:125], v[162:165], v[192:195], v[122:125]
	v_mfma_f32_16x16x32_bf16 v[110:113], v[134:137], v[200:203], v[110:113]
	v_mfma_f32_16x16x32_bf16 v[106:109], v[162:165], v[200:203], v[106:109]
	v_mfma_f32_16x16x32_bf16 v[94:97], v[134:137], v[214:217], v[94:97]
	v_mfma_f32_16x16x32_bf16 v[90:93], v[162:165], v[214:217], v[90:93]
	v_mfma_f32_16x16x32_bf16 v[78:81], v[134:137], v[222:225], v[78:81]
	v_mfma_f32_16x16x32_bf16 v[74:77], v[162:165], v[222:225], v[74:77]
	v_mfma_f32_16x16x32_bf16 v[118:121], v[166:169], v[188:191], v[118:121]
	v_mfma_f32_16x16x32_bf16 v[114:117], v[180:183], v[188:191], v[114:117]
	v_mfma_f32_16x16x32_bf16 v[102:105], v[166:169], v[196:199], v[102:105]
	v_mfma_f32_16x16x32_bf16 v[98:101], v[180:183], v[196:199], v[98:101]
	v_mfma_f32_16x16x32_bf16 v[86:89], v[166:169], v[210:213], v[86:89]
	v_mfma_f32_16x16x32_bf16 v[82:85], v[180:183], v[210:213], v[82:85]
	v_mfma_f32_16x16x32_bf16 v[70:73], v[166:169], v[218:221], v[70:73]
	v_mfma_f32_16x16x32_bf16 v[66:69], v[180:183], v[218:221], v[66:69]
	v_mfma_f32_16x16x32_bf16 v[118:121], v[170:173], v[192:195], v[118:121]
	v_mfma_f32_16x16x32_bf16 v[114:117], v[184:187], v[192:195], v[114:117]
	v_mfma_f32_16x16x32_bf16 v[102:105], v[170:173], v[200:203], v[102:105]
	v_mfma_f32_16x16x32_bf16 v[98:101], v[184:187], v[200:203], v[98:101]
	v_mfma_f32_16x16x32_bf16 v[86:89], v[170:173], v[214:217], v[86:89]
	v_mfma_f32_16x16x32_bf16 v[82:85], v[184:187], v[214:217], v[82:85]
	v_mfma_f32_16x16x32_bf16 v[70:73], v[170:173], v[222:225], v[70:73]
	v_mfma_f32_16x16x32_bf16 v[66:69], v[184:187], v[222:225], v[66:69]
	s_barrier
	s_add_i32 s46, s54, s15
	s_mov_b32 m0, s46
	ds_read_b128 v[188:191], v179 offset:49152
	ds_read_b128 v[192:195], v179 offset:50176
	ds_read_b128 v[196:199], v179 offset:51200
	ds_read_b128 v[200:203], v179 offset:52224
	ds_read_b128 v[210:213], v179 offset:53248
	ds_read_b128 v[214:217], v179 offset:54272
	ds_read_b128 v[218:221], v179 offset:55296
	ds_read_b128 v[222:225], v179 offset:56320
	global_load_lds_dwordx4 v142, s[98:99]
	s_add_i32 m0, s46, 0x2000
	s_add_u32 s22, s22, 0x80080
	s_addc_u32 s23, s23, 0
	s_add_i32 s46, s55, s15
	global_load_lds_dwordx4 v138, s[98:99]
	s_mov_b32 m0, s46
	s_nop 0
	global_load_lds_dwordx4 v142, s[22:23]
	s_add_i32 m0, s46, 0x2000
	s_nop 0
	global_load_lds_dwordx4 v138, s[22:23]
	s_mov_b32 m0, s49
	s_nop 0
	global_load_lds_dwordx4 v144, s[100:101]
	s_mov_b32 m0, s50
	s_nop 0
	global_load_lds_dwordx4 v140, s[100:101]
	s_waitcnt vmcnt(8) lgkmcnt(0)
	s_barrier
	v_mfma_f32_16x16x32_bf16 v[62:65], v[130:133], v[188:191], v[62:65]
	v_mfma_f32_16x16x32_bf16 v[58:61], v[154:157], v[188:191], v[58:61]
	v_mfma_f32_16x16x32_bf16 v[46:49], v[130:133], v[196:199], v[46:49]
	v_mfma_f32_16x16x32_bf16 v[42:45], v[154:157], v[196:199], v[42:45]
	v_mfma_f32_16x16x32_bf16 v[30:33], v[130:133], v[210:213], v[30:33]
	v_mfma_f32_16x16x32_bf16 v[26:29], v[154:157], v[210:213], v[26:29]
	v_mfma_f32_16x16x32_bf16 v[14:17], v[130:133], v[218:221], v[14:17]
	v_mfma_f32_16x16x32_bf16 v[10:13], v[154:157], v[218:221], v[10:13]
	v_mfma_f32_16x16x32_bf16 v[62:65], v[134:137], v[192:195], v[62:65]
	v_mfma_f32_16x16x32_bf16 v[58:61], v[162:165], v[192:195], v[58:61]
	v_mfma_f32_16x16x32_bf16 v[46:49], v[134:137], v[200:203], v[46:49]
	v_mfma_f32_16x16x32_bf16 v[42:45], v[162:165], v[200:203], v[42:45]
	v_mfma_f32_16x16x32_bf16 v[30:33], v[134:137], v[214:217], v[30:33]
	v_mfma_f32_16x16x32_bf16 v[26:29], v[162:165], v[214:217], v[26:29]
	v_mfma_f32_16x16x32_bf16 v[14:17], v[134:137], v[222:225], v[14:17]
	v_mfma_f32_16x16x32_bf16 v[10:13], v[162:165], v[222:225], v[10:13]
	v_mfma_f32_16x16x32_bf16 v[54:57], v[166:169], v[188:191], v[54:57]
	v_mfma_f32_16x16x32_bf16 v[50:53], v[180:183], v[188:191], v[50:53]
	v_mfma_f32_16x16x32_bf16 v[38:41], v[166:169], v[196:199], v[38:41]
	v_mfma_f32_16x16x32_bf16 v[34:37], v[180:183], v[196:199], v[34:37]
	v_mfma_f32_16x16x32_bf16 v[22:25], v[166:169], v[210:213], v[22:25]
	v_mfma_f32_16x16x32_bf16 v[18:21], v[180:183], v[210:213], v[18:21]
	v_mfma_f32_16x16x32_bf16 v[6:9], v[166:169], v[218:221], v[6:9]
	v_mfma_f32_16x16x32_bf16 v[2:5], v[180:183], v[218:221], v[2:5]
	v_mfma_f32_16x16x32_bf16 v[54:57], v[170:173], v[192:195], v[54:57]
	v_mfma_f32_16x16x32_bf16 v[50:53], v[184:187], v[192:195], v[50:53]
	v_mfma_f32_16x16x32_bf16 v[38:41], v[170:173], v[200:203], v[38:41]
	v_mfma_f32_16x16x32_bf16 v[34:37], v[184:187], v[200:203], v[34:37]
	v_mfma_f32_16x16x32_bf16 v[22:25], v[170:173], v[214:217], v[22:25]
	v_mfma_f32_16x16x32_bf16 v[18:21], v[184:187], v[214:217], v[18:21]
	v_mfma_f32_16x16x32_bf16 v[6:9], v[170:173], v[222:225], v[6:9]
	v_mfma_f32_16x16x32_bf16 v[2:5], v[184:187], v[222:225], v[2:5]
	s_barrier
	s_add_i32 s53, s53, 2
	s_add_u32 s6, s6, 0x100
	s_addc_u32 s7, s7, 0
	s_add_u32 s41, s41, 0x100
	s_addc_u32 s52, s52, 0
	s_cmp_gt_u32 s53, 29
	s_cbranch_scc0 .LBB0_604
	s_setprio 0
	s_and_b64 vcc, exec, s[12:13]
	s_cbranch_vccz .LBB0_607
	s_barrier

.LBB0_728:
	s_add_u32 s42, s22, 0x100
	s_addc_u32 s43, s23, 0
	s_add_i32 s50, 0, 0x10000
	s_cmpk_eq_i32 s25, 0x54
	s_cselect_b32 s49, s21, s43
	s_cselect_b32 s48, s20, s42
	s_cselect_b32 s47, s45, s19
	s_cselect_b32 s46, s44, s18
	s_add_i32 s51, 0, 0x14000
	ds_read_b128 v[42:45], v236
	ds_read_b128 v[46:49], v236 offset:1024
	ds_read_b128 v[50:53], v236 offset:2048
	ds_read_b128 v[54:57], v236 offset:3072
	ds_read_b128 v[154:157], v237
	ds_read_b128 v[168:171], v237 offset:1024
	ds_read_b128 v[172:175], v237 offset:2048
	ds_read_b128 v[180:183], v237 offset:3072
	s_add_i32 m0, s33, 0xc000
	ds_read_b128 v[184:187], v178
	ds_read_b128 v[188:191], v178 offset:1024
	ds_read_b128 v[192:195], v178 offset:2048
	ds_read_b128 v[196:199], v178 offset:3072
	ds_read_b128 v[200:203], v178 offset:4096
	ds_read_b128 v[210:213], v178 offset:5120
	ds_read_b128 v[214:217], v178 offset:6144
	ds_read_b128 v[218:221], v178 offset:7168
	global_load_lds_dwordx4 v164, s[22:23]
	s_add_i32 m0, s33, 0xe000
	s_nop 0
	global_load_lds_dwordx4 v166, s[22:23]
	s_waitcnt vmcnt(8) lgkmcnt(0)
	s_barrier
	v_mfma_f32_16x16x32_bf16 v[142:145], v[42:45], v[184:187], v[142:145]
	v_mfma_f32_16x16x32_bf16 v[138:141], v[50:53], v[184:187], v[138:141]
	v_mfma_f32_16x16x32_bf16 v[126:129], v[42:45], v[192:195], v[126:129]
	v_mfma_f32_16x16x32_bf16 v[122:125], v[50:53], v[192:195], v[122:125]
	v_mfma_f32_16x16x32_bf16 v[110:113], v[42:45], v[200:203], v[110:113]
	v_mfma_f32_16x16x32_bf16 v[106:109], v[50:53], v[200:203], v[106:109]
	v_mfma_f32_16x16x32_bf16 v[94:97], v[42:45], v[214:217], v[94:97]
	v_mfma_f32_16x16x32_bf16 v[90:93], v[50:53], v[214:217], v[90:93]
	v_mfma_f32_16x16x32_bf16 v[142:145], v[46:49], v[188:191], v[142:145]
	v_mfma_f32_16x16x32_bf16 v[138:141], v[54:57], v[188:191], v[138:141]
	v_mfma_f32_16x16x32_bf16 v[126:129], v[46:49], v[196:199], v[126:129]
	v_mfma_f32_16x16x32_bf16 v[122:125], v[54:57], v[196:199], v[122:125]
	v_mfma_f32_16x16x32_bf16 v[110:113], v[46:49], v[210:213], v[110:113]
	v_mfma_f32_16x16x32_bf16 v[106:109], v[54:57], v[210:213], v[106:109]
	v_mfma_f32_16x16x32_bf16 v[94:97], v[46:49], v[218:221], v[94:97]
	v_mfma_f32_16x16x32_bf16 v[90:93], v[54:57], v[218:221], v[90:93]
	v_mfma_f32_16x16x32_bf16 v[134:137], v[154:157], v[184:187], v[134:137]
	v_mfma_f32_16x16x32_bf16 v[130:133], v[172:175], v[184:187], v[130:133]
	v_mfma_f32_16x16x32_bf16 v[118:121], v[154:157], v[192:195], v[118:121]
	v_mfma_f32_16x16x32_bf16 v[114:117], v[172:175], v[192:195], v[114:117]
	v_mfma_f32_16x16x32_bf16 v[102:105], v[154:157], v[200:203], v[102:105]
	v_mfma_f32_16x16x32_bf16 v[98:101], v[172:175], v[200:203], v[98:101]
	v_mfma_f32_16x16x32_bf16 v[86:89], v[154:157], v[214:217], v[86:89]
	v_mfma_f32_16x16x32_bf16 v[82:85], v[172:175], v[214:217], v[82:85]
	v_mfma_f32_16x16x32_bf16 v[134:137], v[168:171], v[188:191], v[134:137]
	v_mfma_f32_16x16x32_bf16 v[130:133], v[180:183], v[188:191], v[130:133]
	v_mfma_f32_16x16x32_bf16 v[118:121], v[168:171], v[196:199], v[118:121]
	v_mfma_f32_16x16x32_bf16 v[114:117], v[180:183], v[196:199], v[114:117]
	v_mfma_f32_16x16x32_bf16 v[102:105], v[168:171], v[210:213], v[102:105]
	v_mfma_f32_16x16x32_bf16 v[98:101], v[180:183], v[210:213], v[98:101]
	v_mfma_f32_16x16x32_bf16 v[86:89], v[168:171], v[218:221], v[86:89]
	v_mfma_f32_16x16x32_bf16 v[82:85], v[180:183], v[218:221], v[82:85]
	s_barrier
	s_add_i32 s22, s50, s16
	s_mov_b32 m0, s22
	ds_read_b128 v[184:187], v178 offset:16384
	ds_read_b128 v[188:191], v178 offset:17408
	ds_read_b128 v[192:195], v178 offset:18432
	ds_read_b128 v[196:199], v178 offset:19456
	ds_read_b128 v[200:203], v178 offset:20480
	ds_read_b128 v[210:213], v178 offset:21504
	ds_read_b128 v[214:217], v178 offset:22528
	ds_read_b128 v[218:221], v178 offset:23552
	global_load_lds_dwordx4 v0, s[46:47]
	s_add_i32 m0, s22, 0x2000
	s_add_u32 s22, s46, 0x160000
	s_addc_u32 s23, s47, 0
	s_add_i32 s50, s51, s16
	global_load_lds_dwordx4 v158, s[46:47]
	s_mov_b32 m0, s50
	s_nop 0
	global_load_lds_dwordx4 v0, s[22:23]
	s_add_i32 m0, s50, 0x2000
	s_nop 0
	global_load_lds_dwordx4 v158, s[22:23]
	s_mov_b32 m0, s33
	s_nop 0
	global_load_lds_dwordx4 v162, s[48:49]
	s_mov_b32 m0, s37
	s_nop 0
	global_load_lds_dwordx4 v160, s[48:49]
	s_add_u32 s98, s46, 0x80
	s_addc_u32 s99, s47, 0
	s_add_u32 s100, s48, 0x80
	s_addc_u32 s101, s49, 0
	s_waitcnt vmcnt(8) lgkmcnt(0)
	s_barrier
	v_mfma_f32_16x16x32_bf16 v[78:81], v[42:45], v[184:187], v[78:81]
	v_mfma_f32_16x16x32_bf16 v[74:77], v[50:53], v[184:187], v[74:77]
	v_mfma_f32_16x16x32_bf16 v[62:65], v[42:45], v[192:195], v[62:65]
	v_mfma_f32_16x16x32_bf16 v[58:61], v[50:53], v[192:195], v[58:61]
	v_mfma_f32_16x16x32_bf16 v[30:33], v[42:45], v[200:203], v[30:33]
	v_mfma_f32_16x16x32_bf16 v[26:29], v[50:53], v[200:203], v[26:29]
	v_mfma_f32_16x16x32_bf16 v[14:17], v[42:45], v[214:217], v[14:17]
	v_mfma_f32_16x16x32_bf16 v[10:13], v[50:53], v[214:217], v[10:13]
	v_mfma_f32_16x16x32_bf16 v[78:81], v[46:49], v[188:191], v[78:81]
	v_mfma_f32_16x16x32_bf16 v[74:77], v[54:57], v[188:191], v[74:77]
	v_mfma_f32_16x16x32_bf16 v[62:65], v[46:49], v[196:199], v[62:65]
	v_mfma_f32_16x16x32_bf16 v[58:61], v[54:57], v[196:199], v[58:61]
	v_mfma_f32_16x16x32_bf16 v[30:33], v[46:49], v[210:213], v[30:33]
	v_mfma_f32_16x16x32_bf16 v[26:29], v[54:57], v[210:213], v[26:29]
	v_mfma_f32_16x16x32_bf16 v[14:17], v[46:49], v[218:221], v[14:17]
	v_mfma_f32_16x16x32_bf16 v[10:13], v[54:57], v[218:221], v[10:13]
	v_mfma_f32_16x16x32_bf16 v[38:41], v[154:157], v[192:195], v[38:41]
	v_mfma_f32_16x16x32_bf16 v[34:37], v[172:175], v[192:195], v[34:37]
	v_mfma_f32_16x16x32_bf16 v[22:25], v[154:157], v[200:203], v[22:25]
	v_mfma_f32_16x16x32_bf16 v[18:21], v[172:175], v[200:203], v[18:21]
	v_mfma_f32_16x16x32_bf16 v[6:9], v[154:157], v[214:217], v[6:9]
	v_mfma_f32_16x16x32_bf16 v[2:5], v[172:175], v[214:217], v[2:5]
	v_mfma_f32_16x16x32_bf16 v[42:45], v[154:157], v[184:187], v[70:73]
	v_mfma_f32_16x16x32_bf16 v[46:49], v[172:175], v[184:187], v[66:69]
	v_mfma_f32_16x16x32_bf16 v[38:41], v[168:171], v[196:199], v[38:41]
	v_mfma_f32_16x16x32_bf16 v[34:37], v[180:183], v[196:199], v[34:37]
	v_mfma_f32_16x16x32_bf16 v[22:25], v[168:171], v[210:213], v[22:25]
	v_mfma_f32_16x16x32_bf16 v[18:21], v[180:183], v[210:213], v[18:21]
	v_mfma_f32_16x16x32_bf16 v[6:9], v[168:171], v[218:221], v[6:9]
	v_mfma_f32_16x16x32_bf16 v[2:5], v[180:183], v[218:221], v[2:5]
	v_mfma_f32_16x16x32_bf16 v[42:45], v[168:171], v[188:191], v[42:45]
	v_mfma_f32_16x16x32_bf16 v[46:49], v[180:183], v[188:191], v[46:49]
	s_barrier
	s_add_i32 s50, 0, 0x18000
	s_add_i32 s51, 0, 0x1c000
	ds_read_b128 v[50:53], v238
	ds_read_b128 v[54:57], v238 offset:1024
	ds_read_b128 v[66:69], v238 offset:2048
	ds_read_b128 v[70:73], v238 offset:3072
	ds_read_b128 v[154:157], v239
	ds_read_b128 v[168:171], v239 offset:1024
	ds_read_b128 v[172:175], v239 offset:2048
	ds_read_b128 v[180:183], v239 offset:3072
	s_add_u32 s22, s48, 0x160000
	s_addc_u32 s23, s49, 0
	s_mov_b32 m0, s52
	ds_read_b128 v[184:187], v178 offset:32768
	ds_read_b128 v[188:191], v178 offset:33792
	ds_read_b128 v[192:195], v178 offset:34816
	ds_read_b128 v[196:199], v178 offset:35840
	ds_read_b128 v[200:203], v178 offset:36864
	ds_read_b128 v[210:213], v178 offset:37888
	ds_read_b128 v[214:217], v178 offset:38912
	ds_read_b128 v[218:221], v178 offset:39936
	global_load_lds_dwordx4 v162, s[22:23]
	s_mov_b32 m0, s53
	s_nop 0
	global_load_lds_dwordx4 v160, s[22:23]
	s_waitcnt vmcnt(8) lgkmcnt(0)
	s_barrier
	v_mfma_f32_16x16x32_bf16 v[142:145], v[50:53], v[184:187], v[142:145]
	v_mfma_f32_16x16x32_bf16 v[138:141], v[66:69], v[184:187], v[138:141]
	v_mfma_f32_16x16x32_bf16 v[126:129], v[50:53], v[192:195], v[126:129]
	v_mfma_f32_16x16x32_bf16 v[122:125], v[66:69], v[192:195], v[122:125]
	v_mfma_f32_16x16x32_bf16 v[110:113], v[50:53], v[200:203], v[110:113]
	v_mfma_f32_16x16x32_bf16 v[106:109], v[66:69], v[200:203], v[106:109]
	v_mfma_f32_16x16x32_bf16 v[94:97], v[50:53], v[214:217], v[94:97]
	v_mfma_f32_16x16x32_bf16 v[90:93], v[66:69], v[214:217], v[90:93]
	v_mfma_f32_16x16x32_bf16 v[142:145], v[54:57], v[188:191], v[142:145]
	v_mfma_f32_16x16x32_bf16 v[138:141], v[70:73], v[188:191], v[138:141]
	v_mfma_f32_16x16x32_bf16 v[126:129], v[54:57], v[196:199], v[126:129]
	v_mfma_f32_16x16x32_bf16 v[122:125], v[70:73], v[196:199], v[122:125]
	v_mfma_f32_16x16x32_bf16 v[110:113], v[54:57], v[210:213], v[110:113]
	v_mfma_f32_16x16x32_bf16 v[106:109], v[70:73], v[210:213], v[106:109]
	v_mfma_f32_16x16x32_bf16 v[94:97], v[54:57], v[218:221], v[94:97]
	v_mfma_f32_16x16x32_bf16 v[90:93], v[70:73], v[218:221], v[90:93]
	v_mfma_f32_16x16x32_bf16 v[134:137], v[154:157], v[184:187], v[134:137]
	v_mfma_f32_16x16x32_bf16 v[130:133], v[172:175], v[184:187], v[130:133]
	v_mfma_f32_16x16x32_bf16 v[118:121], v[154:157], v[192:195], v[118:121]
	v_mfma_f32_16x16x32_bf16 v[114:117], v[172:175], v[192:195], v[114:117]
	v_mfma_f32_16x16x32_bf16 v[102:105], v[154:157], v[200:203], v[102:105]
	v_mfma_f32_16x16x32_bf16 v[98:101], v[172:175], v[200:203], v[98:101]
	v_mfma_f32_16x16x32_bf16 v[86:89], v[154:157], v[214:217], v[86:89]
	v_mfma_f32_16x16x32_bf16 v[82:85], v[172:175], v[214:217], v[82:85]
	v_mfma_f32_16x16x32_bf16 v[134:137], v[168:171], v[188:191], v[134:137]
	v_mfma_f32_16x16x32_bf16 v[130:133], v[180:183], v[188:191], v[130:133]
	v_mfma_f32_16x16x32_bf16 v[118:121], v[168:171], v[196:199], v[118:121]
	v_mfma_f32_16x16x32_bf16 v[114:117], v[180:183], v[196:199], v[114:117]
	v_mfma_f32_16x16x32_bf16 v[102:105], v[168:171], v[210:213], v[102:105]
	v_mfma_f32_16x16x32_bf16 v[98:101], v[180:183], v[210:213], v[98:101]
	v_mfma_f32_16x16x32_bf16 v[86:89], v[168:171], v[218:221], v[86:89]
	v_mfma_f32_16x16x32_bf16 v[82:85], v[180:183], v[218:221], v[82:85]
	s_barrier
	s_add_i32 s22, s50, s16
	s_mov_b32 m0, s22
	ds_read_b128 v[184:187], v178 offset:49152
	ds_read_b128 v[188:191], v178 offset:50176
	ds_read_b128 v[192:195], v178 offset:51200
	ds_read_b128 v[196:199], v178 offset:52224
	ds_read_b128 v[200:203], v178 offset:53248
	ds_read_b128 v[210:213], v178 offset:54272
	ds_read_b128 v[214:217], v178 offset:55296
	ds_read_b128 v[218:221], v178 offset:56320
	global_load_lds_dwordx4 v0, s[98:99]
	s_add_i32 m0, s22, 0x2000
	s_add_u32 s22, s46, 0x160080
	s_addc_u32 s23, s47, 0
	s_add_i32 s46, s51, s16
	global_load_lds_dwordx4 v158, s[98:99]
	s_mov_b32 m0, s46
	s_nop 0
	global_load_lds_dwordx4 v0, s[22:23]
	s_add_i32 m0, s46, 0x2000
	s_nop 0
	global_load_lds_dwordx4 v158, s[22:23]
	s_mov_b32 m0, s55
	s_nop 0
	global_load_lds_dwordx4 v162, s[100:101]
	s_mov_b32 m0, s56
	s_nop 0
	global_load_lds_dwordx4 v160, s[100:101]
	s_waitcnt vmcnt(8) lgkmcnt(0)
	s_barrier
	v_mfma_f32_16x16x32_bf16 v[78:81], v[50:53], v[184:187], v[78:81]
	v_mfma_f32_16x16x32_bf16 v[74:77], v[66:69], v[184:187], v[74:77]
	v_mfma_f32_16x16x32_bf16 v[62:65], v[50:53], v[192:195], v[62:65]
	v_mfma_f32_16x16x32_bf16 v[58:61], v[66:69], v[192:195], v[58:61]
	v_mfma_f32_16x16x32_bf16 v[30:33], v[50:53], v[200:203], v[30:33]
	v_mfma_f32_16x16x32_bf16 v[26:29], v[66:69], v[200:203], v[26:29]
	v_mfma_f32_16x16x32_bf16 v[14:17], v[50:53], v[214:217], v[14:17]
	v_mfma_f32_16x16x32_bf16 v[10:13], v[66:69], v[214:217], v[10:13]
	v_mfma_f32_16x16x32_bf16 v[78:81], v[54:57], v[188:191], v[78:81]
	v_mfma_f32_16x16x32_bf16 v[74:77], v[70:73], v[188:191], v[74:77]
	v_mfma_f32_16x16x32_bf16 v[62:65], v[54:57], v[196:199], v[62:65]
	v_mfma_f32_16x16x32_bf16 v[58:61], v[70:73], v[196:199], v[58:61]
	v_mfma_f32_16x16x32_bf16 v[30:33], v[54:57], v[210:213], v[30:33]
	v_mfma_f32_16x16x32_bf16 v[26:29], v[70:73], v[210:213], v[26:29]
	v_mfma_f32_16x16x32_bf16 v[14:17], v[54:57], v[218:221], v[14:17]
	v_mfma_f32_16x16x32_bf16 v[10:13], v[70:73], v[218:221], v[10:13]
	v_mfma_f32_16x16x32_bf16 v[42:45], v[154:157], v[184:187], v[42:45]
	v_mfma_f32_16x16x32_bf16 v[70:73], v[168:171], v[188:191], v[42:45]
	v_mfma_f32_16x16x32_bf16 v[42:45], v[172:175], v[184:187], v[46:49]
	v_mfma_f32_16x16x32_bf16 v[38:41], v[154:157], v[192:195], v[38:41]
	v_mfma_f32_16x16x32_bf16 v[34:37], v[172:175], v[192:195], v[34:37]
	v_mfma_f32_16x16x32_bf16 v[22:25], v[154:157], v[200:203], v[22:25]
	v_mfma_f32_16x16x32_bf16 v[18:21], v[172:175], v[200:203], v[18:21]
	v_mfma_f32_16x16x32_bf16 v[6:9], v[154:157], v[214:217], v[6:9]
	v_mfma_f32_16x16x32_bf16 v[2:5], v[172:175], v[214:217], v[2:5]
	v_mfma_f32_16x16x32_bf16 v[66:69], v[180:183], v[188:191], v[42:45]
	v_mfma_f32_16x16x32_bf16 v[38:41], v[168:171], v[196:199], v[38:41]
	v_mfma_f32_16x16x32_bf16 v[34:37], v[180:183], v[196:199], v[34:37]
	v_mfma_f32_16x16x32_bf16 v[22:25], v[168:171], v[210:213], v[22:25]
	v_mfma_f32_16x16x32_bf16 v[18:21], v[180:183], v[210:213], v[18:21]
	v_mfma_f32_16x16x32_bf16 v[6:9], v[168:171], v[218:221], v[6:9]
	v_mfma_f32_16x16x32_bf16 v[2:5], v[180:183], v[218:221], v[2:5]
	s_barrier
	s_add_i32 s25, s25, 2
	s_add_u32 s18, s18, 0x100
	s_addc_u32 s19, s19, 0
	s_cmpk_gt_u32 s25, 0x55
	s_mov_b64 s[22:23], s[42:43]
	s_cbranch_scc0 .LBB0_728
	s_setprio 0
	s_and_b64 vcc, exec, s[12:13]
	s_cbranch_vccz .LBB0_731
	s_barrier
